# SSD scan items: softplus(dt) and chunk cumulative decay computed once per item into an LDS table instead of per wave per chunk
# baseline (speedup 1.0000x reference)
.LBB0_555:
	s_lshr_b32 s16, s47, 6
	s_lshl_b32 s35, s16, 9
	s_add_i32 s71, s35, 0
	s_lshr_b32 s49, s47, 7
	s_lshr_b32 s35, s47, 5
	s_andn2_b32 s47, s47, 63
	s_add_i32 s73, s47, 0
	s_add_i32 s71, s71, 0x19c00
	s_lshl_b32 s72, s49, 4
	s_and_b32 s51, s35, 2
	s_add_i32 s73, s73, 0x19800
	s_lshl_b32 s81, s16, 5
	s_lshl_b64 s[40:41], s[42:43], 1
	s_add_u32 s36, s28, s40
	s_addc_u32 s37, s29, s41
	s_add_u32 s38, s38, s40
	s_addc_u32 s39, s39, s41
	s_lshl_b64 s[40:41], s[30:31], 1
	s_add_u32 s40, s28, s40
	s_addc_u32 s41, s29, s41
	s_lshl_b32 s82, s46, 6
	s_lshl_b64 s[42:43], s[42:43], 2
	s_add_u32 s74, s13, s42
	s_addc_u32 s75, s50, s43
	s_lshl_b32 s12, s12, 1
	s_add_u32 s42, s28, s12
	s_addc_u32 s43, s29, 0
	s_lshl_b32 s12, s48, 2
	s_add_u32 s44, s44, s12
	s_addc_u32 s45, s45, 0
	s_lshl_b32 s76, s16, 4
	s_cmp_le_u32 s51, s49
	s_cselect_b64 s[46:47], -1, 0
	s_lshl_b32 s77, s51, 4
	s_or_b32 s12, s51, 1
	s_cmp_lt_u32 s51, s49
	v_mov_b32_e32 v20, v21
	s_cselect_b64 s[48:49], -1, 0
	s_add_i32 s81, s81, 0
	v_mov_b32_e32 v22, v21
	v_mov_b32_e32 v23, v21
	v_mov_b64_e32 v[0:1], v[20:21]
	v_mov_b64_e32 v[4:5], v[20:21]
	v_mov_b64_e32 v[8:9], v[20:21]
	v_mov_b64_e32 v[12:13], v[20:21]
	s_mov_b32 s35, s17
	s_lshl_b32 s78, s12, 4
	s_lshl_b32 s79, s51, 5
	s_lshl_b32 s80, s12, 5
	s_add_i32 s81, s81, 0x8800
	s_or_b32 s82, s82, 1
	s_mov_b32 s83, 0
	v_mov_b64_e32 v[2:3], v[22:23]
	v_mov_b64_e32 v[6:7], v[22:23]
	v_mov_b64_e32 v[10:11], v[22:23]
	v_mov_b64_e32 v[14:15], v[22:23]
	s_and_b64 vcc, exec, s[10:11]
	s_cbranch_vccz .Lpc_skip
	v_and_b32_e32 v150, 63, v192
	v_mov_b32_e32 v173, 0
	s_add_i32 s88, s16, 0
	s_lshl_b32 s89, s88, 6
	s_add_i32 s89, s89, s69
	v_add_u32_e32 v172, s89, v150
	v_lshlrev_b64 v[174:175], 7, v[172:173]
	v_lshl_add_u64 v[174:175], s[44:45], 0, v[174:175]
	global_load_dword v164, v[174:175], off offset:64
	s_add_i32 s88, s16, 8
	s_lshl_b32 s89, s88, 6
	s_add_i32 s89, s89, s69
	v_add_u32_e32 v172, s89, v150
	v_lshlrev_b64 v[174:175], 7, v[172:173]
	v_lshl_add_u64 v[174:175], s[44:45], 0, v[174:175]
	global_load_dword v165, v[174:175], off offset:64
	s_add_i32 s88, s16, 16
	s_lshl_b32 s89, s88, 6
	s_add_i32 s89, s89, s69
	v_add_u32_e32 v172, s89, v150
	v_lshlrev_b64 v[174:175], 7, v[172:173]
	v_lshl_add_u64 v[174:175], s[44:45], 0, v[174:175]
	global_load_dword v166, v[174:175], off offset:64
	s_add_i32 s88, s16, 24
	s_lshl_b32 s89, s88, 6
	s_add_i32 s89, s89, s69
	v_add_u32_e32 v172, s89, v150
	v_lshlrev_b64 v[174:175], 7, v[172:173]
	v_lshl_add_u64 v[174:175], s[44:45], 0, v[174:175]
	global_load_dword v167, v[174:175], off offset:64
	s_add_i32 s88, s16, 32
	s_lshl_b32 s89, s88, 6
	s_add_i32 s89, s89, s69
	v_add_u32_e32 v172, s89, v150
	v_lshlrev_b64 v[174:175], 7, v[172:173]
	v_lshl_add_u64 v[174:175], s[44:45], 0, v[174:175]
	global_load_dword v168, v[174:175], off offset:64
	s_add_i32 s88, s16, 40
	s_lshl_b32 s89, s88, 6
	s_add_i32 s89, s89, s69
	v_add_u32_e32 v172, s89, v150
	v_lshlrev_b64 v[174:175], 7, v[172:173]
	v_lshl_add_u64 v[174:175], s[44:45], 0, v[174:175]
	global_load_dword v169, v[174:175], off offset:64
	s_add_i32 s88, s16, 48
	s_lshl_b32 s89, s88, 6
	s_add_i32 s89, s89, s69
	v_add_u32_e32 v172, s89, v150
	v_lshlrev_b64 v[174:175], 7, v[172:173]
	v_lshl_add_u64 v[174:175], s[44:45], 0, v[174:175]
	global_load_dword v170, v[174:175], off offset:64
	s_add_i32 s88, s16, 56
	s_lshl_b32 s89, s88, 6
	s_add_i32 s89, s89, s69
	v_add_u32_e32 v172, s89, v150
	v_lshlrev_b64 v[174:175], 7, v[172:173]
	v_lshl_add_u64 v[174:175], s[44:45], 0, v[174:175]
	global_load_dword v171, v[174:175], off offset:64
	v_lshlrev_b32_e32 v151, 2, v150
	s_lshl_b32 s88, s16, 9
	s_add_i32 s88, s88, 0x1e400
	v_add_u32_e32 v151, s88, v151
	s_waitcnt vmcnt(7)
	v_add_f32_e32 v156, v125, v164
	v_mul_f32_e32 v157, 0x3fb8aa3b, v156
	v_exp_f32_e32 v157, v157
	v_mov_b32_e32 v159, 0
	v_add_f32_e32 v157, 1.0, v157
	v_cmp_gt_f32_e32 vcc, s56, v157
	s_nop 1
	v_cndmask_b32_e64 v158, 0, 32, vcc
	v_ldexp_f32 v157, v157, v158
	v_log_f32_e32 v157, v157
	v_cndmask_b32_e32 v160, 0, v123, vcc
	v_mov_b32_e32 v158, 0
	v_mul_f32_e32 v161, 0x3f317217, v157
	v_fma_f32 v161, v157, s57, -v161
	v_fmac_f32_e32 v161, 0x3377d1cf, v157
	v_fmac_f32_e32 v161, 0x3f317217, v157
	v_cmp_lt_f32_e64 vcc, |v157|, s58
	s_nop 1
	v_cndmask_b32_e32 v157, v157, v161, vcc
	v_sub_f32_e32 v157, v157, v160
	v_cmp_lt_f32_e32 vcc, s55, v156
	s_nop 1
	v_cndmask_b32_e32 v156, v157, v156, vcc
	v_mul_f32_e32 v157, v126, v156
	s_nop 1
	v_mov_b32_dpp v157, v157 row_shr:1 row_mask:0xf bank_mask:0xf bound_ctrl:1
	v_fmac_f32_e32 v157, v126, v156
	s_nop 1
	v_add_f32_dpp v157, v157, v157 row_shr:2 row_mask:0xf bank_mask:0xf bound_ctrl:1
	s_nop 1
	v_add_f32_dpp v157, v157, v157 row_shr:4 row_mask:0xf bank_mask:0xf bound_ctrl:1
	s_nop 1
	v_add_f32_dpp v157, v157, v157 row_shr:8 row_mask:0xf bank_mask:0xf bound_ctrl:1
	s_nop 1
	v_mov_b32_dpp v158, v157 row_bcast:15 row_mask:0xa bank_mask:0xf bound_ctrl:1
	v_add_f32_e32 v157, v157, v158
	s_nop 1
	v_mov_b32_dpp v159, v157 row_bcast:31 row_mask:0xc bank_mask:0xf bound_ctrl:1
	v_add_f32_e32 v162, v157, v159
	ds_write2st64_b32 v151, v156, v162 offset1:1
	v_add_u32_e32 v151, 0x1000, v151
	s_waitcnt vmcnt(6)
	v_add_f32_e32 v156, v125, v165
	v_mul_f32_e32 v157, 0x3fb8aa3b, v156
	v_exp_f32_e32 v157, v157
	v_mov_b32_e32 v159, 0
	v_add_f32_e32 v157, 1.0, v157
	v_cmp_gt_f32_e32 vcc, s56, v157
	s_nop 1
	v_cndmask_b32_e64 v158, 0, 32, vcc
	v_ldexp_f32 v157, v157, v158
	v_log_f32_e32 v157, v157
	v_cndmask_b32_e32 v160, 0, v123, vcc
	v_mov_b32_e32 v158, 0
	v_mul_f32_e32 v161, 0x3f317217, v157
	v_fma_f32 v161, v157, s57, -v161
	v_fmac_f32_e32 v161, 0x3377d1cf, v157
	v_fmac_f32_e32 v161, 0x3f317217, v157
	v_cmp_lt_f32_e64 vcc, |v157|, s58
	s_nop 1
	v_cndmask_b32_e32 v157, v157, v161, vcc
	v_sub_f32_e32 v157, v157, v160
	v_cmp_lt_f32_e32 vcc, s55, v156
	s_nop 1
	v_cndmask_b32_e32 v156, v157, v156, vcc
	v_mul_f32_e32 v157, v126, v156
	s_nop 1
	v_mov_b32_dpp v157, v157 row_shr:1 row_mask:0xf bank_mask:0xf bound_ctrl:1
	v_fmac_f32_e32 v157, v126, v156
	s_nop 1
	v_add_f32_dpp v157, v157, v157 row_shr:2 row_mask:0xf bank_mask:0xf bound_ctrl:1
	s_nop 1
	v_add_f32_dpp v157, v157, v157 row_shr:4 row_mask:0xf bank_mask:0xf bound_ctrl:1
	s_nop 1
	v_add_f32_dpp v157, v157, v157 row_shr:8 row_mask:0xf bank_mask:0xf bound_ctrl:1
	s_nop 1
	v_mov_b32_dpp v158, v157 row_bcast:15 row_mask:0xa bank_mask:0xf bound_ctrl:1
	v_add_f32_e32 v157, v157, v158
	s_nop 1
	v_mov_b32_dpp v159, v157 row_bcast:31 row_mask:0xc bank_mask:0xf bound_ctrl:1
	v_add_f32_e32 v162, v157, v159
	ds_write2st64_b32 v151, v156, v162 offset1:1
	v_add_u32_e32 v151, 0x1000, v151
	s_waitcnt vmcnt(5)
	v_add_f32_e32 v156, v125, v166
	v_mul_f32_e32 v157, 0x3fb8aa3b, v156
	v_exp_f32_e32 v157, v157
	v_mov_b32_e32 v159, 0
	v_add_f32_e32 v157, 1.0, v157
	v_cmp_gt_f32_e32 vcc, s56, v157
	s_nop 1
	v_cndmask_b32_e64 v158, 0, 32, vcc
	v_ldexp_f32 v157, v157, v158
	v_log_f32_e32 v157, v157
	v_cndmask_b32_e32 v160, 0, v123, vcc
	v_mov_b32_e32 v158, 0
	v_mul_f32_e32 v161, 0x3f317217, v157
	v_fma_f32 v161, v157, s57, -v161
	v_fmac_f32_e32 v161, 0x3377d1cf, v157
	v_fmac_f32_e32 v161, 0x3f317217, v157
	v_cmp_lt_f32_e64 vcc, |v157|, s58
	s_nop 1
	v_cndmask_b32_e32 v157, v157, v161, vcc
	v_sub_f32_e32 v157, v157, v160
	v_cmp_lt_f32_e32 vcc, s55, v156
	s_nop 1
	v_cndmask_b32_e32 v156, v157, v156, vcc
	v_mul_f32_e32 v157, v126, v156
	s_nop 1
	v_mov_b32_dpp v157, v157 row_shr:1 row_mask:0xf bank_mask:0xf bound_ctrl:1
	v_fmac_f32_e32 v157, v126, v156
	s_nop 1
	v_add_f32_dpp v157, v157, v157 row_shr:2 row_mask:0xf bank_mask:0xf bound_ctrl:1
	s_nop 1
	v_add_f32_dpp v157, v157, v157 row_shr:4 row_mask:0xf bank_mask:0xf bound_ctrl:1
	s_nop 1
	v_add_f32_dpp v157, v157, v157 row_shr:8 row_mask:0xf bank_mask:0xf bound_ctrl:1
	s_nop 1
	v_mov_b32_dpp v158, v157 row_bcast:15 row_mask:0xa bank_mask:0xf bound_ctrl:1
	v_add_f32_e32 v157, v157, v158
	s_nop 1
	v_mov_b32_dpp v159, v157 row_bcast:31 row_mask:0xc bank_mask:0xf bound_ctrl:1
	v_add_f32_e32 v162, v157, v159
	ds_write2st64_b32 v151, v156, v162 offset1:1
	v_add_u32_e32 v151, 0x1000, v151
	s_waitcnt vmcnt(4)
	v_add_f32_e32 v156, v125, v167
	v_mul_f32_e32 v157, 0x3fb8aa3b, v156
	v_exp_f32_e32 v157, v157
	v_mov_b32_e32 v159, 0
	v_add_f32_e32 v157, 1.0, v157
	v_cmp_gt_f32_e32 vcc, s56, v157
	s_nop 1
	v_cndmask_b32_e64 v158, 0, 32, vcc
	v_ldexp_f32 v157, v157, v158
	v_log_f32_e32 v157, v157
	v_cndmask_b32_e32 v160, 0, v123, vcc
	v_mov_b32_e32 v158, 0
	v_mul_f32_e32 v161, 0x3f317217, v157
	v_fma_f32 v161, v157, s57, -v161
	v_fmac_f32_e32 v161, 0x3377d1cf, v157
	v_fmac_f32_e32 v161, 0x3f317217, v157
	v_cmp_lt_f32_e64 vcc, |v157|, s58
	s_nop 1
	v_cndmask_b32_e32 v157, v157, v161, vcc
	v_sub_f32_e32 v157, v157, v160
	v_cmp_lt_f32_e32 vcc, s55, v156
	s_nop 1
	v_cndmask_b32_e32 v156, v157, v156, vcc
	v_mul_f32_e32 v157, v126, v156
	s_nop 1
	v_mov_b32_dpp v157, v157 row_shr:1 row_mask:0xf bank_mask:0xf bound_ctrl:1
	v_fmac_f32_e32 v157, v126, v156
	s_nop 1
	v_add_f32_dpp v157, v157, v157 row_shr:2 row_mask:0xf bank_mask:0xf bound_ctrl:1
	s_nop 1
	v_add_f32_dpp v157, v157, v157 row_shr:4 row_mask:0xf bank_mask:0xf bound_ctrl:1
	s_nop 1
	v_add_f32_dpp v157, v157, v157 row_shr:8 row_mask:0xf bank_mask:0xf bound_ctrl:1
	s_nop 1
	v_mov_b32_dpp v158, v157 row_bcast:15 row_mask:0xa bank_mask:0xf bound_ctrl:1
	v_add_f32_e32 v157, v157, v158
	s_nop 1
	v_mov_b32_dpp v159, v157 row_bcast:31 row_mask:0xc bank_mask:0xf bound_ctrl:1
	v_add_f32_e32 v162, v157, v159
	ds_write2st64_b32 v151, v156, v162 offset1:1
	v_add_u32_e32 v151, 0x1000, v151
	s_waitcnt vmcnt(3)
	v_add_f32_e32 v156, v125, v168
	v_mul_f32_e32 v157, 0x3fb8aa3b, v156
	v_exp_f32_e32 v157, v157
	v_mov_b32_e32 v159, 0
	v_add_f32_e32 v157, 1.0, v157
	v_cmp_gt_f32_e32 vcc, s56, v157
	s_nop 1
	v_cndmask_b32_e64 v158, 0, 32, vcc
	v_ldexp_f32 v157, v157, v158
	v_log_f32_e32 v157, v157
	v_cndmask_b32_e32 v160, 0, v123, vcc
	v_mov_b32_e32 v158, 0
	v_mul_f32_e32 v161, 0x3f317217, v157
	v_fma_f32 v161, v157, s57, -v161
	v_fmac_f32_e32 v161, 0x3377d1cf, v157
	v_fmac_f32_e32 v161, 0x3f317217, v157
	v_cmp_lt_f32_e64 vcc, |v157|, s58
	s_nop 1
	v_cndmask_b32_e32 v157, v157, v161, vcc
	v_sub_f32_e32 v157, v157, v160
	v_cmp_lt_f32_e32 vcc, s55, v156
	s_nop 1
	v_cndmask_b32_e32 v156, v157, v156, vcc
	v_mul_f32_e32 v157, v126, v156
	s_nop 1
	v_mov_b32_dpp v157, v157 row_shr:1 row_mask:0xf bank_mask:0xf bound_ctrl:1
	v_fmac_f32_e32 v157, v126, v156
	s_nop 1
	v_add_f32_dpp v157, v157, v157 row_shr:2 row_mask:0xf bank_mask:0xf bound_ctrl:1
	s_nop 1
	v_add_f32_dpp v157, v157, v157 row_shr:4 row_mask:0xf bank_mask:0xf bound_ctrl:1
	s_nop 1
	v_add_f32_dpp v157, v157, v157 row_shr:8 row_mask:0xf bank_mask:0xf bound_ctrl:1
	s_nop 1
	v_mov_b32_dpp v158, v157 row_bcast:15 row_mask:0xa bank_mask:0xf bound_ctrl:1
	v_add_f32_e32 v157, v157, v158
	s_nop 1
	v_mov_b32_dpp v159, v157 row_bcast:31 row_mask:0xc bank_mask:0xf bound_ctrl:1
	v_add_f32_e32 v162, v157, v159
	ds_write2st64_b32 v151, v156, v162 offset1:1
	v_add_u32_e32 v151, 0x1000, v151
	s_waitcnt vmcnt(2)
	v_add_f32_e32 v156, v125, v169
	v_mul_f32_e32 v157, 0x3fb8aa3b, v156
	v_exp_f32_e32 v157, v157
	v_mov_b32_e32 v159, 0
	v_add_f32_e32 v157, 1.0, v157
	v_cmp_gt_f32_e32 vcc, s56, v157
	s_nop 1
	v_cndmask_b32_e64 v158, 0, 32, vcc
	v_ldexp_f32 v157, v157, v158
	v_log_f32_e32 v157, v157
	v_cndmask_b32_e32 v160, 0, v123, vcc
	v_mov_b32_e32 v158, 0
	v_mul_f32_e32 v161, 0x3f317217, v157
	v_fma_f32 v161, v157, s57, -v161
	v_fmac_f32_e32 v161, 0x3377d1cf, v157
	v_fmac_f32_e32 v161, 0x3f317217, v157
	v_cmp_lt_f32_e64 vcc, |v157|, s58
	s_nop 1
	v_cndmask_b32_e32 v157, v157, v161, vcc
	v_sub_f32_e32 v157, v157, v160
	v_cmp_lt_f32_e32 vcc, s55, v156
	s_nop 1
	v_cndmask_b32_e32 v156, v157, v156, vcc
	v_mul_f32_e32 v157, v126, v156
	s_nop 1
	v_mov_b32_dpp v157, v157 row_shr:1 row_mask:0xf bank_mask:0xf bound_ctrl:1
	v_fmac_f32_e32 v157, v126, v156
	s_nop 1
	v_add_f32_dpp v157, v157, v157 row_shr:2 row_mask:0xf bank_mask:0xf bound_ctrl:1
	s_nop 1
	v_add_f32_dpp v157, v157, v157 row_shr:4 row_mask:0xf bank_mask:0xf bound_ctrl:1
	s_nop 1
	v_add_f32_dpp v157, v157, v157 row_shr:8 row_mask:0xf bank_mask:0xf bound_ctrl:1
	s_nop 1
	v_mov_b32_dpp v158, v157 row_bcast:15 row_mask:0xa bank_mask:0xf bound_ctrl:1
	v_add_f32_e32 v157, v157, v158
	s_nop 1
	v_mov_b32_dpp v159, v157 row_bcast:31 row_mask:0xc bank_mask:0xf bound_ctrl:1
	v_add_f32_e32 v162, v157, v159
	ds_write2st64_b32 v151, v156, v162 offset1:1
	v_add_u32_e32 v151, 0x1000, v151
	s_waitcnt vmcnt(1)
	v_add_f32_e32 v156, v125, v170
	v_mul_f32_e32 v157, 0x3fb8aa3b, v156
	v_exp_f32_e32 v157, v157
	v_mov_b32_e32 v159, 0
	v_add_f32_e32 v157, 1.0, v157
	v_cmp_gt_f32_e32 vcc, s56, v157
	s_nop 1
	v_cndmask_b32_e64 v158, 0, 32, vcc
	v_ldexp_f32 v157, v157, v158
	v_log_f32_e32 v157, v157
	v_cndmask_b32_e32 v160, 0, v123, vcc
	v_mov_b32_e32 v158, 0
	v_mul_f32_e32 v161, 0x3f317217, v157
	v_fma_f32 v161, v157, s57, -v161
	v_fmac_f32_e32 v161, 0x3377d1cf, v157
	v_fmac_f32_e32 v161, 0x3f317217, v157
	v_cmp_lt_f32_e64 vcc, |v157|, s58
	s_nop 1
	v_cndmask_b32_e32 v157, v157, v161, vcc
	v_sub_f32_e32 v157, v157, v160
	v_cmp_lt_f32_e32 vcc, s55, v156
	s_nop 1
	v_cndmask_b32_e32 v156, v157, v156, vcc
	v_mul_f32_e32 v157, v126, v156
	s_nop 1
	v_mov_b32_dpp v157, v157 row_shr:1 row_mask:0xf bank_mask:0xf bound_ctrl:1
	v_fmac_f32_e32 v157, v126, v156
	s_nop 1
	v_add_f32_dpp v157, v157, v157 row_shr:2 row_mask:0xf bank_mask:0xf bound_ctrl:1
	s_nop 1
	v_add_f32_dpp v157, v157, v157 row_shr:4 row_mask:0xf bank_mask:0xf bound_ctrl:1
	s_nop 1
	v_add_f32_dpp v157, v157, v157 row_shr:8 row_mask:0xf bank_mask:0xf bound_ctrl:1
	s_nop 1
	v_mov_b32_dpp v158, v157 row_bcast:15 row_mask:0xa bank_mask:0xf bound_ctrl:1
	v_add_f32_e32 v157, v157, v158
	s_nop 1
	v_mov_b32_dpp v159, v157 row_bcast:31 row_mask:0xc bank_mask:0xf bound_ctrl:1
	v_add_f32_e32 v162, v157, v159
	ds_write2st64_b32 v151, v156, v162 offset1:1
	v_add_u32_e32 v151, 0x1000, v151
	s_waitcnt vmcnt(0)
	v_add_f32_e32 v156, v125, v171
	v_mul_f32_e32 v157, 0x3fb8aa3b, v156
	v_exp_f32_e32 v157, v157
	v_mov_b32_e32 v159, 0
	v_add_f32_e32 v157, 1.0, v157
	v_cmp_gt_f32_e32 vcc, s56, v157
	s_nop 1
	v_cndmask_b32_e64 v158, 0, 32, vcc
	v_ldexp_f32 v157, v157, v158
	v_log_f32_e32 v157, v157
	v_cndmask_b32_e32 v160, 0, v123, vcc
	v_mov_b32_e32 v158, 0
	v_mul_f32_e32 v161, 0x3f317217, v157
	v_fma_f32 v161, v157, s57, -v161
	v_fmac_f32_e32 v161, 0x3377d1cf, v157
	v_fmac_f32_e32 v161, 0x3f317217, v157
	v_cmp_lt_f32_e64 vcc, |v157|, s58
	s_nop 1
	v_cndmask_b32_e32 v157, v157, v161, vcc
	v_sub_f32_e32 v157, v157, v160
	v_cmp_lt_f32_e32 vcc, s55, v156
	s_nop 1
	v_cndmask_b32_e32 v156, v157, v156, vcc
	v_mul_f32_e32 v157, v126, v156
	s_nop 1
	v_mov_b32_dpp v157, v157 row_shr:1 row_mask:0xf bank_mask:0xf bound_ctrl:1
	v_fmac_f32_e32 v157, v126, v156
	s_nop 1
	v_add_f32_dpp v157, v157, v157 row_shr:2 row_mask:0xf bank_mask:0xf bound_ctrl:1
	s_nop 1
	v_add_f32_dpp v157, v157, v157 row_shr:4 row_mask:0xf bank_mask:0xf bound_ctrl:1
	s_nop 1
	v_add_f32_dpp v157, v157, v157 row_shr:8 row_mask:0xf bank_mask:0xf bound_ctrl:1
	s_nop 1
	v_mov_b32_dpp v158, v157 row_bcast:15 row_mask:0xa bank_mask:0xf bound_ctrl:1
	v_add_f32_e32 v157, v157, v158
	s_nop 1
	v_mov_b32_dpp v159, v157 row_bcast:31 row_mask:0xc bank_mask:0xf bound_ctrl:1
	v_add_f32_e32 v162, v157, v159
	ds_write2st64_b32 v151, v156, v162 offset1:1
	s_mov_b32 s71, 0x1e400
.Lpc_skip:
	s_waitcnt lgkmcnt(0)
	s_waitcnt vmcnt(0)
	s_barrier
	s_branch .LBB0_557
.LBB0_556:
	s_waitcnt vmcnt(0)
	v_mov_b64_e32 v[94:95], v[18:19]
	v_mov_b64_e32 v[88:89], v[96:97]
	v_mov_b64_e32 v[24:25], v[56:57]
	v_mov_b64_e32 v[92:93], v[16:17]
	v_mov_b64_e32 v[90:91], v[98:99]
	v_mov_b64_e32 v[26:27], v[58:59]
	v_mov_b64_e32 v[28:29], v[60:61]
	v_mov_b64_e32 v[30:31], v[62:63]
	v_mov_b64_e32 v[32:33], v[64:65]
	v_mov_b64_e32 v[34:35], v[66:67]
	v_mov_b64_e32 v[36:37], v[68:69]
	v_mov_b64_e32 v[38:39], v[70:71]
	v_mov_b64_e32 v[40:41], v[72:73]
	v_mov_b64_e32 v[42:43], v[74:75]
	v_mov_b64_e32 v[44:45], v[76:77]
	v_mov_b64_e32 v[46:47], v[78:79]
	v_mov_b64_e32 v[48:49], v[80:81]
	v_mov_b64_e32 v[50:51], v[82:83]
	v_mov_b64_e32 v[52:53], v[84:85]
	v_mov_b64_e32 v[54:55], v[86:87]
	s_add_i32 s69, s69, 64
	s_addk_i32 s71, 0x200
	s_add_i32 s83, s83, 1
	s_cmp_lg_u32 s83, 64
	s_cbranch_scc0 .LBB0_534

.LBB0_561:
	s_andn2_b64 vcc, exec, s[12:13]
	v_and_b32_e32 v111, 63, v113
	s_cbranch_vccnz .LBB0_565
	v_ashrrev_i32_e32 v63, 4, v113
	v_lshlrev_b32_e32 v58, 16, v27
	v_and_b32_e32 v59, 0xffff0000, v27
	v_cmp_lt_i32_e32 vcc, s65, v113
	v_ashrrev_i32_e32 v150, 3, v113
	v_lshl_add_u32 v150, v150, 2, s71
	v_lshl_add_u32 v151, v63, 2, s71
	v_lshl_add_u32 v152, v111, 2, s71
	ds_read_b32 v20, v150
	ds_read_b32 v154, v151 offset:256
	ds_read_b32 v155, v151 offset:384
	ds_read_b32 v60, v152 offset:256
	v_ashrrev_i32_e32 v17, 3, v113
	v_lshlrev_b32_e32 v16, 4, v113
	v_mul_lo_u32 v61, v17, s54
	v_and_b32_e32 v62, 0x70, v16
	v_add3_u32 v18, s59, v61, v62
	v_and_b32_e32 v16, 0xf0, v16
	ds_write_b128 v18, v[92:95]
	v_add3_u32 v18, s64, v61, v62
	v_add_u32_e32 v16, 0, v16
	ds_write_b128 v18, v[24:27]
	v_mad_u64_u32 v[22:23], s[12:13], v63, s53, v[16:17]
	v_add_u32_e32 v18, 0x200, v113
	v_ashrrev_i32_e32 v23, 4, v18
	v_mad_u64_u32 v[56:57], s[12:13], v23, s53, v[16:17]
	ds_write_b128 v22, v[28:31] offset:17408
	ds_write_b128 v22, v[36:39]
	ds_write_b128 v56, v[32:35] offset:17408
	ds_write_b128 v56, v[40:43]
	v_lshlrev_b32_e32 v16, 16, v24
	v_and_b32_e32 v17, 0xffff0000, v24
	v_lshlrev_b32_e32 v18, 16, v25
	v_and_b32_e32 v19, 0xffff0000, v25
	s_waitcnt lgkmcnt(6)
	v_pk_mul_f32 v[16:17], v[20:21], v[16:17] op_sel_hi:[0,1]
	v_pk_mul_f32 v[18:19], v[20:21], v[18:19] op_sel_hi:[0,1]
	v_cvt_pk_bf16_f32 v16, v16, v17
	v_cvt_pk_bf16_f32 v17, v18, v19
	v_lshlrev_b32_e32 v18, 16, v26
	v_and_b32_e32 v19, 0xffff0000, v26
	v_pk_mul_f32 v[18:19], v[20:21], v[18:19] op_sel_hi:[0,1]
	v_pk_mul_f32 v[58:59], v[20:21], v[58:59] op_sel_hi:[0,1]
	v_cvt_pk_bf16_f32 v18, v18, v19
	v_cvt_pk_bf16_f32 v19, v58, v59
	v_add3_u32 v20, 0, v61, v62
	ds_write_b128 v20, v[16:19] offset:52224
	v_readlane_b32 s16, v60, 63
	v_and_b32_e32 v17, 0xffff0000, v28
	v_lshlrev_b32_e32 v18, 16, v29
	v_and_b32_e32 v19, 0xffff0000, v29
	v_sub_f32_e32 v16, s16, v154
	v_mul_f32_e32 v16, 0x3fb8aa3b, v16
	v_exp_f32_e32 v20, v16
	v_lshlrev_b32_e32 v16, 16, v28
	v_lshlrev_b32_e32 v58, 16, v31
	v_and_b32_e32 v59, 0xffff0000, v31
	v_pk_mul_f32 v[16:17], v[20:21], v[16:17] op_sel_hi:[0,1]
	v_pk_mul_f32 v[18:19], v[20:21], v[18:19] op_sel_hi:[0,1]
	v_cvt_pk_bf16_f32 v16, v16, v17
	v_cvt_pk_bf16_f32 v17, v18, v19
	v_lshlrev_b32_e32 v18, 16, v30
	v_and_b32_e32 v19, 0xffff0000, v30
	v_pk_mul_f32 v[18:19], v[20:21], v[18:19] op_sel_hi:[0,1]
	v_pk_mul_f32 v[58:59], v[20:21], v[58:59] op_sel_hi:[0,1]
	v_cvt_pk_bf16_f32 v18, v18, v19
	v_cvt_pk_bf16_f32 v19, v58, v59
	ds_write_b128 v22, v[16:19] offset:34816
	v_and_b32_e32 v17, 0xffff0000, v32
	v_lshlrev_b32_e32 v18, 16, v33
	v_and_b32_e32 v19, 0xffff0000, v33
	v_lshlrev_b32_e32 v22, 16, v35
	v_sub_f32_e32 v16, s16, v155
	v_mul_f32_e32 v16, 0x3fb8aa3b, v16
	v_exp_f32_e32 v20, v16
	v_lshlrev_b32_e32 v16, 16, v32
	v_and_b32_e32 v23, 0xffff0000, v35
	v_pk_mul_f32 v[16:17], v[20:21], v[16:17] op_sel_hi:[0,1]
	v_pk_mul_f32 v[18:19], v[20:21], v[18:19] op_sel_hi:[0,1]
	v_cvt_pk_bf16_f32 v16, v16, v17
	v_cvt_pk_bf16_f32 v17, v18, v19
	v_lshlrev_b32_e32 v18, 16, v34
	v_and_b32_e32 v19, 0xffff0000, v34
	v_pk_mul_f32 v[18:19], v[20:21], v[18:19] op_sel_hi:[0,1]
	v_pk_mul_f32 v[22:23], v[20:21], v[22:23] op_sel_hi:[0,1]
	v_cvt_pk_bf16_f32 v18, v18, v19
	v_cvt_pk_bf16_f32 v19, v22, v23
	ds_write_b128 v56, v[16:19] offset:34816
	s_and_saveexec_b64 s[12:13], vcc
	s_cbranch_execz .LBB0_564
	v_mul_f32_e32 v16, s16, v124
	v_exp_f32_e32 v16, v16
	s_add_i32 s16, 0, 0x19800
	v_lshl_add_u32 v17, v113, 2, s16
	v_add_u32_e32 v17, 0xfffffa00, v17
	ds_write_b32 v17, v16

.LBB0_687:
	v_or_b32_e32 v16, s76, v109
	v_lshlrev_b32_e32 v17, 1, v107
	v_mul_lo_u32 v16, v16, s54
	v_add3_u32 v16, s67, v17, v16
	v_cvt_pk_bf16_f32 v17, v1, s0
	s_barrier
	ds_write_b16 v16, v17 offset:144
	v_cvt_pk_bf16_f32 v17, v2, s0
	ds_write_b16 v16, v17 offset:288
	v_cvt_pk_bf16_f32 v17, v3, s0
	ds_write_b16 v16, v17 offset:432
	v_cvt_pk_bf16_f32 v17, v4, s0
	ds_write_b16 v16, v17 offset:32
	v_cvt_pk_bf16_f32 v17, v5, s0
	ds_write_b16 v16, v17 offset:176
	v_cvt_pk_bf16_f32 v17, v6, s0
	ds_write_b16 v16, v17 offset:320
	v_cvt_pk_bf16_f32 v17, v7, s0
	ds_write_b16 v16, v17 offset:464
	v_cvt_pk_bf16_f32 v17, v8, s0
	ds_write_b16 v16, v17 offset:64
	v_cvt_pk_bf16_f32 v17, v9, s0
	ds_write_b16 v16, v17 offset:208
	v_cvt_pk_bf16_f32 v17, v10, s0
	ds_write_b16 v16, v17 offset:352
	v_cvt_pk_bf16_f32 v17, v11, s0
	ds_write_b16 v16, v17 offset:496
	v_cvt_pk_bf16_f32 v17, v12, s0
	ds_write_b16 v16, v17 offset:96
	v_cvt_pk_bf16_f32 v17, v13, s0
	ds_write_b16 v16, v17 offset:240
	v_cvt_pk_bf16_f32 v17, v14, s0
	v_cvt_pk_bf16_f32 v18, v0, s0
	ds_write_b16 v16, v17 offset:384
	v_cvt_pk_bf16_f32 v17, v15, s0
	ds_write_b16 v16, v18
	ds_write_b16 v16, v17 offset:528
	s_add_i32 s69, s69, 64
	s_addk_i32 s71, 0x200
	s_add_i32 s83, s83, 1
	s_cmp_lg_u32 s83, 64
	s_cbranch_scc1 .LBB0_557
	s_branch .LBB0_534
